# barrier-4 fast path: per-pm XCC mask and mismatch word prefetched with scalar loads into s100/s101 instead of sc1 vector loads
# speedup vs baseline: 1.0338x; 1.0338x over previous
.LBB0_243:
	s_or_b64 exec, exec, s[0:1]
	s_waitcnt lgkmcnt(0)
	v_mov_b32_e32 v0, v254
	s_barrier
	s_and_b32 s4, s2, 7
	s_lshl_b32 s4, s4, 3
	s_bfe_u32 s5, s2, 0x30003
	s_add_i32 s4, s4, s5
	s_lshl_b32 s4, s4, 6
	s_add_i32 s4, s4, 0x5000
	s_load_dword s100, s[52:53], s4
	s_mov_b32 s0, 0x46800000
	v_and_b32_e32 v1, 63, v0
	v_lshlrev_b32_e32 v1, 2, v1
	global_load_dword v2, v1, s[24:25]
	global_load_dword v3, v1, s[26:27]
	global_load_dword v4, v1, s[36:37]
	global_load_dword v5, v1, s[38:39]
	global_load_dword v6, v1, s[20:21]
	global_load_dword v7, v1, s[22:23]
	v_mbcnt_lo_u32_b32 v1, -1, 0
	v_mbcnt_hi_u32_b32 v1, -1, v1
	v_and_b32_e32 v8, 64, v1
	v_xor_b32_e32 v9, 1, v1
	v_add_u32_e32 v8, 64, v8
	v_xor_b32_e32 v10, 2, v1
	v_cmp_lt_i32_e32 vcc, v9, v8
	v_xor_b32_e32 v11, 4, v1
	v_xor_b32_e32 v12, 8, v1
	v_cndmask_b32_e32 v9, v1, v9, vcc
	v_cmp_lt_i32_e32 vcc, v10, v8
	v_xor_b32_e32 v13, 16, v1
	v_xor_b32_e32 v14, 32, v1
	v_cndmask_b32_e32 v10, v1, v10, vcc
	v_cmp_lt_i32_e32 vcc, v11, v8
	s_add_u32 s38, s52, 0x3800000
	s_addc_u32 s44, s53, 0
	v_cndmask_b32_e32 v11, v1, v11, vcc
	v_cmp_lt_i32_e32 vcc, v12, v8
	s_add_u32 s45, s52, 0x4800000
	s_addc_u32 s46, s53, 0
	v_cndmask_b32_e32 v12, v1, v12, vcc
	v_cmp_lt_i32_e32 vcc, v13, v8
	s_add_u32 s47, s52, 0x5800000
	s_addc_u32 s48, s53, 0
	v_cndmask_b32_e32 v13, v1, v13, vcc
	v_cmp_lt_i32_e32 vcc, v14, v8
	v_lshlrev_b32_e32 v8, 2, v9
	v_lshlrev_b32_e32 v9, 2, v10
	v_cndmask_b32_e32 v1, v1, v14, vcc
	v_lshlrev_b32_e32 v10, 2, v11
	v_lshlrev_b32_e32 v11, 2, v12
	v_lshlrev_b32_e32 v193, 2, v13
	v_lshlrev_b32_e32 v194, 2, v1
	s_add_u32 s49, s52, 0x6800000
	s_addc_u32 s50, s53, 0
	s_add_u32 s51, s52, 0x7800000
	s_addc_u32 s56, s53, 0
	s_add_u32 s57, s52, 0x8800000
	s_addc_u32 s58, s53, 0
	s_add_u32 s16, s52, 0xb800000
	s_mov_b32 s21, 0
	s_mov_b32 s39, 0x3fb8aa3b
	s_addc_u32 s17, s53, 0
	v_mov_b32_e32 v131, 0
	s_add_i32 s63, 0, 0x20040
	s_movk_i32 s64, 0x70
	v_mov_b32_e32 v195, 0x358637bd
	s_mov_b32 s65, 0x800000
	s_movk_i32 s66, 0xffef
	s_movk_i32 s67, 0xffe7
	v_mov_b32_e32 v196, 0x3f80
	v_mov_b32_e32 v197, 0x3f803f80
	v_mov_b32_e32 v198, 0x42800000
	v_mov_b32_e32 v199, 0xc6ea6000
	s_waitcnt vmcnt(4)
	v_mul_f32_e32 v1, v2, v3
	ds_bpermute_b32 v1, v8, v1
	s_waitcnt vmcnt(2)
	v_mul_f32_e32 v12, v4, v5
	s_waitcnt vmcnt(1)
	v_and_b32_e32 v13, 0x7fffffff, v6
	s_waitcnt vmcnt(0)
	v_and_b32_e32 v14, 0x7fffffff, v7
	ds_bpermute_b32 v12, v8, v12
	ds_bpermute_b32 v13, v8, v13
	ds_bpermute_b32 v8, v8, v14
	v_max_f32_e64 v6, |v6|, |v6|
	s_waitcnt lgkmcnt(3)
	v_fmac_f32_e32 v1, v2, v3
	s_waitcnt lgkmcnt(2)
	v_fmac_f32_e32 v12, v4, v5
	s_waitcnt lgkmcnt(1)
	v_max_f32_e32 v2, v13, v13
	v_max_f32_e64 v7, |v7|, |v7|
	s_waitcnt lgkmcnt(0)
	v_max_f32_e32 v3, v8, v8
	ds_bpermute_b32 v4, v9, v1
	ds_bpermute_b32 v5, v9, v12
	v_max_f32_e32 v2, v6, v2
	v_max_f32_e32 v3, v7, v3
	ds_bpermute_b32 v6, v9, v2
	ds_bpermute_b32 v7, v9, v3
	s_waitcnt lgkmcnt(3)
	v_add_f32_e32 v1, v1, v4
	s_waitcnt lgkmcnt(2)
	v_add_f32_e32 v4, v12, v5
	ds_bpermute_b32 v5, v10, v1
	ds_bpermute_b32 v8, v10, v4
	s_waitcnt lgkmcnt(3)
	v_max_f32_e32 v6, v6, v6
	s_waitcnt lgkmcnt(2)
	v_max_f32_e32 v7, v7, v7
	v_max_f32_e32 v2, v2, v6
	v_max_f32_e32 v3, v3, v7
	ds_bpermute_b32 v6, v10, v2
	ds_bpermute_b32 v7, v10, v3
	s_waitcnt lgkmcnt(3)
	v_add_f32_e32 v1, v1, v5
	s_waitcnt lgkmcnt(2)
	v_add_f32_e32 v4, v4, v8
	ds_bpermute_b32 v5, v11, v1
	ds_bpermute_b32 v8, v11, v4
	s_waitcnt lgkmcnt(3)
	v_max_f32_e32 v6, v6, v6
	s_waitcnt lgkmcnt(2)
	v_max_f32_e32 v7, v7, v7
	v_max_f32_e32 v2, v2, v6
	v_max_f32_e32 v3, v3, v7
	ds_bpermute_b32 v6, v11, v2
	ds_bpermute_b32 v7, v11, v3
	s_waitcnt lgkmcnt(3)
	v_add_f32_e32 v1, v1, v5
	s_waitcnt lgkmcnt(2)
	v_add_f32_e32 v4, v4, v8
	ds_bpermute_b32 v5, v193, v1
	ds_bpermute_b32 v8, v193, v4
	s_waitcnt lgkmcnt(3)
	v_max_f32_e32 v6, v6, v6
	s_waitcnt lgkmcnt(2)
	v_max_f32_e32 v7, v7, v7
	v_max_f32_e32 v2, v2, v6
	v_max_f32_e32 v3, v3, v7
	ds_bpermute_b32 v6, v193, v2
	ds_bpermute_b32 v7, v193, v3
	s_waitcnt lgkmcnt(3)
	v_add_f32_e32 v1, v1, v5
	s_waitcnt lgkmcnt(2)
	v_add_f32_e32 v4, v4, v8
	ds_bpermute_b32 v5, v194, v1
	ds_bpermute_b32 v8, v194, v4
	s_waitcnt lgkmcnt(3)
	v_max_f32_e32 v6, v6, v6
	s_waitcnt lgkmcnt(2)
	v_max_f32_e32 v7, v7, v7
	v_max_f32_e32 v2, v2, v6
	v_max_f32_e32 v3, v3, v7
	s_waitcnt lgkmcnt(1)
	v_add_f32_e32 v1, v1, v5
	s_waitcnt lgkmcnt(0)
	v_add_f32_e32 v4, v4, v8
	ds_bpermute_b32 v5, v194, v2
	ds_bpermute_b32 v6, v194, v3
	v_mul_f32_e32 v1, 0x3fb8aa3b, v1
	v_mul_f32_e32 v4, 0x3fb8aa3b, v4
	v_exp_f32_e32 v1, v1
	v_exp_f32_e32 v4, v4
	s_waitcnt lgkmcnt(1)
	v_max_f32_e32 v5, v5, v5
	s_waitcnt lgkmcnt(0)
	v_max_f32_e32 v6, v6, v6
	v_max_f32_e32 v2, v2, v5
	v_sub_f32_e32 v1, v1, v4
	v_max_f32_e32 v3, v3, v6
	v_add_f32_e32 v180, 0x3e4ccccd, v1
	v_mul_f32_e32 v1, 0x41000000, v2
	v_mul_f32_e32 v1, v1, v3
	v_mul_f32_e32 v1, 0x3f828f5c, v1
	v_mov_b32_e32 v2, 0x41c80000
	v_fmac_f32_e32 v2, 2.0, v1
	v_mul_f32_e32 v1, 4.0, v2
	v_ceil_f32_e32 v1, v1
	v_mov_b32_e32 v3, 0x46800000
	v_cmp_nle_f32_e32 vcc, s0, v1
	v_mov_b32_e32 v181, v180
	s_nop 0
	v_cndmask_b32_e32 v1, v3, v1, vcc
	s_nop 0
	v_readfirstlane_b32 s59, v1
	v_mul_f32_e32 v1, 0x41800000, v2
	v_ceil_f32_e32 v1, v1
	v_cmp_nle_f32_e32 vcc, s0, v1
	s_nop 1
	v_cndmask_b32_e32 v1, v3, v1, vcc
	s_nop 0
	v_readfirstlane_b32 s60, v1
	v_mul_f32_e32 v1, 0x42800000, v2
	v_ceil_f32_e32 v1, v1
	v_cmp_nle_f32_e32 vcc, s0, v1
	s_nop 1
	v_cndmask_b32_e32 v1, v3, v1, vcc
	s_nop 0
	v_readfirstlane_b32 s61, v1
	v_mul_f32_e32 v1, 0x43800000, v2
	v_ceil_f32_e32 v1, v1
	v_cmp_nle_f32_e32 vcc, s0, v1
	v_cmp_eq_u32_e64 s[0:1], 0, v0
	s_nop 0
	v_cndmask_b32_e32 v1, v3, v1, vcc
	s_nop 0
	v_readfirstlane_b32 s62, v1
	s_branch .LBB0_246

.Lxa_w0:
	s_bcnt1_i32_b32 s5, s100
	s_cmp_eq_u32 s5, 1
	s_cbranch_scc1 .Lxa_skip
	s_mov_b64 s[8:9], exec
	s_mov_b64 exec, 1
	v_mov_b32_e32 v208, 0x7000
	v_mov_b32_e32 v209, 1
	global_atomic_add v208, v209, s[52:53]
	s_mov_b64 exec, s[8:9]

.LBB0_363:
	s_or_b64 exec, exec, s[0:1]
	s_waitcnt vmcnt(1)
	v_mov_b32_e32 v144, v254
	s_waitcnt lgkmcnt(0)
	v_cndmask_b32_e64 v240, 0, 1, s[94:95]
	s_barrier
	s_load_dword s101, s[52:53], 0x7000
	s_cmpk_gt_u32 s2, 0xff
	s_cbranch_scc1 .Lxb_done
	v_readfirstlane_b32 s4, v254
	s_nop 0
	s_lshr_b32 s4, s4, 6
	s_cmp_lg_u32 s4, 0
	s_cbranch_scc1 .Lxb_low
	global_load_dwordx4 v[124:127], v200, s[12:13] nt
	global_load_dwordx4 v[120:123], v200, s[12:13] offset:16 nt
	global_load_dwordx4 v[116:119], v200, s[12:13] offset:128 nt
	global_load_dwordx4 v[112:115], v200, s[12:13] offset:144 nt
	global_load_dwordx4 v[108:111], v201, s[12:13] nt
	global_load_dwordx4 v[104:107], v201, s[12:13] offset:16 nt
	global_load_dwordx4 v[100:103], v201, s[12:13] offset:128 nt
	global_load_dwordx4 v[96:99], v201, s[12:13] offset:144 nt
	global_load_dwordx4 v[92:95], v202, s[12:13] nt
	global_load_dwordx4 v[88:91], v202, s[12:13] offset:16 nt
	global_load_dwordx4 v[84:87], v202, s[12:13] offset:128 nt
	global_load_dwordx4 v[80:83], v202, s[12:13] offset:144 nt
	global_load_dwordx4 v[76:79], v203, s[12:13] nt
	global_load_dwordx4 v[72:75], v203, s[12:13] offset:16 nt
	global_load_dwordx4 v[68:71], v203, s[12:13] offset:128 nt
	global_load_dwordx4 v[64:67], v203, s[12:13] offset:144 nt
	global_load_dwordx4 v[60:63], v204, s[12:13] nt
	global_load_dwordx4 v[56:59], v204, s[12:13] offset:16 nt
	global_load_dwordx4 v[52:55], v204, s[12:13] offset:128 nt
	global_load_dwordx4 v[48:51], v204, s[12:13] offset:144 nt
	global_load_dwordx4 v[44:47], v205, s[12:13] nt
	global_load_dwordx4 v[40:43], v205, s[12:13] offset:16 nt
	global_load_dwordx4 v[36:39], v205, s[12:13] offset:128 nt
	global_load_dwordx4 v[32:35], v205, s[12:13] offset:144 nt
	global_load_dwordx4 v[28:31], v206, s[12:13] nt
	global_load_dwordx4 v[24:27], v206, s[12:13] offset:16 nt
	global_load_dwordx4 v[20:23], v206, s[12:13] offset:128 nt

.LBB0_405:
	s_waitcnt vmcnt(0)
	s_waitcnt lgkmcnt(0)
	s_barrier
	s_and_saveexec_b64 s[4:5], s[92:93]
	s_cbranch_execz .LBB0_457
	s_cmpk_gt_u32 s2, 0xff
	s_cbranch_scc1 .Lgb_slow
	s_cmp_lg_u32 s101, 0
	s_cbranch_scc1 .Lgb_slow
	s_and_b32 s8, s2, 7
	s_lshl_b32 s8, s8, 3
	s_bfe_u32 s9, s2, 0x30003
	s_add_i32 s8, s8, s9
	s_lshl_b32 s8, s8, 6
	s_add_i32 s8, s8, 0x6000
	v_mov_b32_e32 v0, s8
	v_mov_b32_e32 v1, 1
	global_atomic_add v0, v1, s[52:53]
	s_mov_b32 s9, 0
